# phase 1: half of each XCD's workgroups run the filter items before norm0 (others norm0 first), overlapping HBM streaming with matrix-core work
# speedup vs baseline: 1.0258x; 1.0038x over previous
.LBB0_6:
	s_cmpk_lt_i32 s2, 0x1000
	s_load_dwordx16 s[16:31], s[0:1], 0xc0
	s_mov_b32 s6, s2
	s_cselect_b64 s[2:3], -1, 0
	v_writelane_b32 v251, s2, 18
	s_load_dwordx16 s[36:51], s[0:1], 0x0
	s_mov_b32 s7, 0
	v_writelane_b32 v251, s3, 19
	s_add_u32 s2, s0, 0x108
	s_addc_u32 s3, s1, 0
	s_waitcnt lgkmcnt(0)
	s_add_u32 s20, s30, 0x12900000
	v_writelane_b32 v251, s2, 20
	s_addc_u32 s21, s31, 0
	v_lshrrev_b32_e32 v1, 20, v0
	v_writelane_b32 v251, s3, 21
	s_add_u32 s2, s30, 0x1700000
	s_addc_u32 s3, s31, 0
	v_writelane_b32 v251, s2, 22
	v_lshrrev_b32_e32 v0, 10, v0
	v_or_b32_e32 v0, v0, v1
	v_writelane_b32 v251, s3, 23
	s_and_b32 s2, s6, 7
	v_writelane_b32 v251, s2, 24
	s_lshr_b32 s2, s6, 3
	v_writelane_b32 v251, s2, 25
	s_add_u32 s2, s30, 0x1a900000
	s_addc_u32 s3, s31, 0
	s_add_u32 s24, s30, 0x2500000
	s_addc_u32 s25, s31, 0
	v_writelane_b32 v251, s2, 26
	s_cmpk_lt_i32 s6, 0x800
	v_and_b32_e32 v2, 63, v179
	v_writelane_b32 v251, s3, 27
	s_cselect_b64 s[2:3], -1, 0
	v_writelane_b32 v251, s2, 28
	s_mov_b64 s[64:65], s[20:21]
	v_lshrrev_b32_e32 v234, 4, v179
	v_writelane_b32 v251, s3, 29
	s_add_u32 s2, s30, 0x1ea00000
	s_addc_u32 s3, s31, 0
	v_writelane_b32 v251, s2, 30
	v_mbcnt_lo_u32_b32 v3, -1, 0
	v_mbcnt_hi_u32_b32 v249, -1, v3
	v_writelane_b32 v251, s3, 31
	s_add_u32 s2, s30, 0x2300000
	s_addc_u32 s3, s31, 0
	v_writelane_b32 v251, s2, 32
	s_lshl_b32 s35, s6, 9
	v_and_b32_e32 v3, 64, v249
	v_writelane_b32 v251, s3, 33
	s_add_u32 s2, s30, 0x1b40000
	s_addc_u32 s3, s31, 0
	v_writelane_b32 v251, s2, 34
	s_cmpk_lt_i32 s6, 0x410
	v_mov_b32_e32 v1, 0
	v_writelane_b32 v251, s3, 35
	s_cselect_b64 s[2:3], -1, 0
	v_writelane_b32 v251, s2, 36
	v_mov_b32_e32 v178, 0x358637bd
	v_mov_b32_e32 v235, 0x1000
	v_writelane_b32 v251, s3, 37
	s_add_u32 s2, s30, 0x1f300000
	s_addc_u32 s3, s31, 0
	v_writelane_b32 v251, s2, 38
	s_cmpk_lt_i32 s6, 0x1040
	v_mov_b32_e32 v196, 0x3000
	v_writelane_b32 v251, s3, 39
	s_cselect_b64 s[2:3], -1, 0
	v_writelane_b32 v251, s2, 40
	v_mov_b32_e32 v197, 0xbf1f24be
	v_mov_b32_e32 v198, 0x3e642e9d
	v_writelane_b32 v251, s3, 41
	s_add_u32 s2, s30, 0xa00000
	s_addc_u32 s3, s31, 0
	v_writelane_b32 v251, s2, 42
	v_mov_b32_e32 v199, 0x1f8
	v_add_u32_e32 v221, 64, v3
	v_writelane_b32 v251, s3, 43
	s_add_u32 s2, s30, 0x1b09000
	s_addc_u32 s3, s31, 0
	v_writelane_b32 v251, s2, 44
	s_cmpk_lt_i32 s6, 0x820
	v_xor_b32_e32 v248, 32, v249
	v_writelane_b32 v251, s3, 45
	s_cselect_b64 s[2:3], -1, 0
	v_writelane_b32 v251, s2, 46
	v_xor_b32_e32 v220, 16, v249
	v_xor_b32_e32 v236, 8, v249
	v_writelane_b32 v251, s3, 47
	s_add_u32 s2, s48, 0x1000
	s_addc_u32 s3, s49, 0
	v_writelane_b32 v251, s2, 48
	v_xor_b32_e32 v237, 4, v249
	v_xor_b32_e32 v216, 2, v249
	v_writelane_b32 v251, s3, 49
	s_add_u32 s2, s30, 0x800000
	s_addc_u32 s3, s31, 0
	s_add_u32 s10, s30, 0x8680000
	v_writelane_b32 v251, s2, 50
	s_addc_u32 s11, s31, 0
	v_xor_b32_e32 v250, 1, v249
	v_writelane_b32 v251, s3, 51
	s_add_u32 s2, s30, 0x1b20000
	s_addc_u32 s3, s31, 0
	v_writelane_b32 v251, s2, 52
	v_mov_b32_e32 v219, 0x7f800000
	v_mov_b32_e32 v238, 0x41b17218
	v_writelane_b32 v251, s3, 53
	s_lshl_b64 s[2:3], s[6:7], 19
	s_add_u32 s4, s30, 0x2100000
	s_addc_u32 s5, s31, 0
	v_writelane_b32 v251, s4, 54
	v_mov_b32_e32 v217, 0xffc00000
	v_mov_b32_e32 v218, 0x7fc00000
	v_writelane_b32 v251, s5, 55
	s_add_u32 s4, s30, s2
	v_writelane_b32 v251, s2, 56
	s_addc_u32 s5, s31, s3
	s_add_u32 s84, s4, 0x16a00000
	s_addc_u32 s85, s5, 0
	s_add_u32 s86, s4, 0x16a20000
	s_addc_u32 s87, s5, 0
	v_writelane_b32 v251, s3, 57
	s_add_u32 s2, s30, 0xc780000
	s_addc_u32 s3, s31, 0
	v_writelane_b32 v251, s2, 58
	s_movk_i32 s4, 0x3ff
	v_and_or_b32 v0, v0, s4, v179
	v_writelane_b32 v251, s3, 59
	s_add_u32 s2, s30, 0xe800000
	v_writelane_b32 v251, s2, 60
	s_addc_u32 s2, s31, 0
	v_writelane_b32 v251, s2, 61
	s_add_u32 s2, s30, 0x10880000
	s_addc_u32 s3, s31, 0
	v_writelane_b32 v251, s2, 62
	s_mov_b64 s[88:89], 0x4000
	s_mov_b32 s90, 0x3e75aa41
	v_writelane_b32 v251, s3, 63
	s_add_u32 s2, s30, 0x1b20004
	s_addc_u32 s3, s31, 0
	v_writelane_b32 v252, s2, 0
	s_mov_b32 s92, 0x40490fdb
	s_mov_b32 s94, 0x3d4be544
	v_writelane_b32 v252, s3, 1
	s_add_u32 s2, s30, 0xa700000
	s_addc_u32 s3, s31, 0
	v_writelane_b32 v252, s2, 2
	s_mov_b32 s96, 0x3ec3ef15
	s_mov_b32 s62, 0x3f6c835e
	v_writelane_b32 v252, s3, 3
	s_add_u32 s2, s30, 0x1b28000
	s_addc_u32 s3, s31, 0
	v_writelane_b32 v252, s2, 4
	s_mov_b32 s80, 0x40234736
	s_mov_b32 s82, 0xc0a55e0e
	v_writelane_b32 v252, s3, 5
	s_add_u32 s2, s30, 0x1b00000
	s_addc_u32 s3, s31, 0
	v_writelane_b32 v252, s2, 6
	s_mov_b32 s60, 0xbfaad1da
	s_nop 0
	v_writelane_b32 v252, s3, 7
	s_add_u32 s2, s30, 0x1c00000
	s_addc_u32 s3, s31, 0
	v_writelane_b32 v252, s2, 8
	s_cmpk_lt_i32 s6, 0x16b2
	s_nop 0
	v_writelane_b32 v252, s3, 9
	s_cselect_b64 s[2:3], -1, 0
	v_writelane_b32 v252, s2, 10
	s_cmp_lt_i32 s58, 0
	s_nop 0
	v_writelane_b32 v252, s3, 11
	s_cselect_b64 s[2:3], -1, 0
	v_writelane_b32 v252, s2, 12
	s_nop 1
	v_writelane_b32 v252, s3, 13
	s_add_u32 s2, s30, 0x1bc0200
	s_addc_u32 s3, s31, 0
	v_writelane_b32 v252, s2, 14
	s_nop 1
	v_writelane_b32 v252, s3, 15
	s_add_u32 s2, s30, 0x1bc0400
	s_addc_u32 s3, s31, 0
	v_writelane_b32 v252, s2, 16
	s_nop 1
	v_writelane_b32 v252, s3, 17
	s_add_u32 s2, s30, 0x1bc0500
	s_addc_u32 s3, s31, 0
	v_writelane_b32 v252, s2, 18
	s_nop 1
	v_writelane_b32 v252, s3, 19
	s_add_u32 s2, s30, 0x1bc0600
	s_addc_u32 s3, s31, 0
	v_writelane_b32 v252, s2, 20
	s_nop 1
	v_writelane_b32 v252, s3, 21
	s_add_u32 s2, s30, 0x1bc0700
	s_addc_u32 s3, s31, 0
	v_writelane_b32 v252, s2, 22
	s_nop 1
	v_writelane_b32 v252, s3, 23
	s_add_u32 s2, s30, 0x1bc0800
	s_addc_u32 s3, s31, 0
	v_writelane_b32 v252, s2, 24
	s_nop 1
	v_writelane_b32 v252, s3, 25
	s_add_u32 s2, s30, 0x1bc0900
	s_addc_u32 s3, s31, 0
	v_writelane_b32 v252, s2, 26
	s_nop 1
	v_writelane_b32 v252, s3, 27
	s_add_u32 s2, s30, 0x1bc0a00
	s_addc_u32 s3, s31, 0
	v_writelane_b32 v252, s2, 28
	s_nop 1
	v_writelane_b32 v252, s3, 29
	s_add_u32 s2, s30, 0x1bc0b00
	s_addc_u32 s3, s31, 0
	v_writelane_b32 v252, s2, 30
	s_nop 1
	v_writelane_b32 v252, s3, 31
	s_add_u32 s2, s30, 0x1bc0c00
	s_addc_u32 s3, s31, 0
	v_writelane_b32 v252, s2, 32
	s_nop 1
	v_writelane_b32 v252, s3, 33
	s_add_u32 s2, s30, 0x1bc0d00
	s_addc_u32 s3, s31, 0
	v_writelane_b32 v252, s2, 34
	s_nop 1
	v_writelane_b32 v252, s3, 35
	s_add_u32 s2, s30, 0x1bc0e00
	s_addc_u32 s3, s31, 0
	v_writelane_b32 v252, s2, 36
	s_nop 1
	v_writelane_b32 v252, s3, 37
	s_add_u32 s2, s30, 0x1bc0f00
	s_addc_u32 s3, s31, 0
	v_writelane_b32 v252, s2, 38
	s_nop 1
	v_writelane_b32 v252, s3, 39
	s_add_u32 s2, s30, 0x1bc1000
	s_addc_u32 s3, s31, 0
	v_writelane_b32 v252, s2, 40
	s_nop 1
	v_writelane_b32 v252, s3, 41
	s_add_u32 s2, s30, 0x1bc1100
	s_addc_u32 s3, s31, 0
	v_writelane_b32 v252, s2, 42
	s_nop 1
	v_writelane_b32 v252, s3, 43
	s_add_u32 s2, s30, 0x1bc1200
	s_addc_u32 s3, s31, 0
	v_writelane_b32 v252, s2, 44
	s_nop 1
	v_writelane_b32 v252, s3, 45
	s_add_u32 s2, s30, 0x1bc1300
	s_addc_u32 s3, s31, 0
	v_writelane_b32 v252, s2, 46
	s_cmp_eq_u32 s8, 15
	s_nop 0
	v_writelane_b32 v252, s3, 47
	s_cselect_b64 s[2:3], -1, 0
	v_writelane_b32 v252, s2, 48
	s_cmp_eq_u32 s8, 14
	s_nop 0
	v_writelane_b32 v252, s3, 49
	s_cselect_b64 s[2:3], -1, 0
	v_writelane_b32 v252, s2, 50
	s_cmp_eq_u32 s8, 13
	s_nop 0
	v_writelane_b32 v252, s3, 51
	s_cselect_b64 s[2:3], -1, 0
	v_writelane_b32 v252, s2, 52
	s_cmp_eq_u32 s8, 12
	s_nop 0
	v_writelane_b32 v252, s3, 53
	s_cselect_b64 s[2:3], -1, 0
	v_writelane_b32 v252, s2, 54
	s_cmp_eq_u32 s8, 11
	s_nop 0
	v_writelane_b32 v252, s3, 55
	s_cselect_b64 s[2:3], -1, 0
	v_writelane_b32 v252, s2, 56
	s_cmp_eq_u32 s8, 10
	s_nop 0
	v_writelane_b32 v252, s3, 57
	s_cselect_b64 s[2:3], -1, 0
	v_writelane_b32 v252, s2, 58
	s_cmp_eq_u32 s8, 9
	s_nop 0
	v_writelane_b32 v252, s3, 59
	s_cselect_b64 s[2:3], -1, 0
	v_writelane_b32 v252, s2, 60
	s_cmp_eq_u32 s8, 8
	s_nop 0
	v_writelane_b32 v252, s3, 61
	s_cselect_b64 s[2:3], -1, 0
	v_writelane_b32 v252, s2, 62
	s_cmp_eq_u32 s8, 7
	s_nop 0
	v_writelane_b32 v252, s3, 63
	s_cselect_b64 s[2:3], -1, 0
	v_writelane_b32 v253, s2, 0
	s_cmp_eq_u32 s8, 6
	s_nop 0
	v_writelane_b32 v253, s3, 1
	s_cselect_b64 s[2:3], -1, 0
	v_writelane_b32 v253, s2, 2
	s_cmp_eq_u32 s8, 5
	s_nop 0
	v_writelane_b32 v253, s3, 3
	s_cselect_b64 s[2:3], -1, 0
	v_writelane_b32 v253, s2, 4
	s_cmp_eq_u32 s8, 4
	s_nop 0
	v_writelane_b32 v253, s3, 5
	s_cselect_b64 s[2:3], -1, 0
	v_writelane_b32 v253, s2, 6
	s_cmp_eq_u32 s8, 3
	s_nop 0
	v_writelane_b32 v253, s3, 7
	s_cselect_b64 s[2:3], -1, 0
	v_writelane_b32 v253, s2, 8
	s_cmp_eq_u32 s8, 2
	s_nop 0
	v_writelane_b32 v253, s3, 9
	s_cselect_b64 s[2:3], -1, 0
	v_writelane_b32 v253, s2, 10
	s_cmp_eq_u32 s8, 1
	s_nop 0
	v_writelane_b32 v253, s3, 11
	s_cselect_b64 s[2:3], -1, 0
	v_writelane_b32 v253, s2, 12
	s_cmp_eq_u32 s8, 0
	s_nop 0
	v_writelane_b32 v253, s3, 13
	s_cselect_b64 s[2:3], -1, 0
	v_writelane_b32 v253, s2, 14
	s_lshl_b32 s4, s8, 8
	s_nop 0
	v_writelane_b32 v253, s3, 15
	s_add_u32 s2, s12, s4
	s_addc_u32 s3, s13, 0
	s_add_u32 s4, s2, 0x1400
	s_addc_u32 s5, s3, 0
	v_writelane_b32 v253, s4, 16
	s_add_u32 s2, s2, 0x2400
	s_addc_u32 s3, s3, 0
	v_writelane_b32 v253, s5, 17
	v_writelane_b32 v253, s2, 18
	s_nop 1
	v_writelane_b32 v253, s3, 19
	s_add_u32 s2, s30, 0x1bc3400
	s_addc_u32 s3, s31, 0
	v_writelane_b32 v253, s2, 20
	s_nop 1
	v_writelane_b32 v253, s3, 21
	s_add_u32 s2, s30, 0x1bc3500
	s_addc_u32 s3, s31, 0
	v_writelane_b32 v253, s2, 22
	s_nop 1
	v_writelane_b32 v253, s3, 23
	s_lshl_b32 s2, s6, 3
	v_writelane_b32 v253, s2, 24
	s_add_u32 s2, s30, 0x12900080
	v_writelane_b32 v253, s2, 25
	s_addc_u32 s2, s31, 0
	v_writelane_b32 v253, s2, 26
	s_add_u32 s2, s30, 0x1700080
	v_writelane_b32 v253, s2, 27
	s_addc_u32 s2, s31, 0
	v_writelane_b32 v253, s2, 28
	s_add_u32 s2, s28, 0x80
	v_writelane_b32 v253, s2, 29
	s_addc_u32 s2, s29, 0
	v_writelane_b32 v253, s2, 30
	s_add_u32 s2, s30, 0xa00080
	v_writelane_b32 v253, s2, 31
	s_addc_u32 s2, s31, 0
	v_writelane_b32 v253, s2, 32
	s_lshl_b32 s2, s6, 4
	v_writelane_b32 v253, s2, 33
	s_add_u32 s2, s30, 0x800080
	v_writelane_b32 v253, s2, 34
	s_addc_u32 s2, s31, 0
	v_writelane_b32 v253, s2, 35
	s_mov_b32 s2, s6
	v_writelane_b32 v253, s2, 36
	s_nop 1
	v_writelane_b32 v253, s3, 37
	s_lshl_b32 s2, s6, 6
	v_writelane_b32 v253, s2, 38
	s_add_u32 s2, s28, 0xfffc
	s_addc_u32 s3, s29, 0
	v_writelane_b32 v253, s2, 39
	s_nop 1
	v_writelane_b32 v253, s3, 40
	s_add_u32 s2, s28, 8
	v_writelane_b32 v253, s2, 41
	s_addc_u32 s2, s29, 0
	v_writelane_b32 v253, s2, 42
	s_add_u32 s2, s30, 0x55c0200
	v_writelane_b32 v253, s2, 43
	s_addc_u32 s2, s31, 0
	v_writelane_b32 v253, s2, 44
	s_add_u32 s2, s30, 0x80
	v_writelane_b32 v253, s2, 45
	s_addc_u32 s2, s31, 0
	v_writelane_b32 v253, s2, 46
	s_add_u32 s2, s44, 0x9000
	v_writelane_b32 v253, s36, 47
	s_addc_u32 s3, s45, 0
	s_nop 0
	v_writelane_b32 v253, s37, 48
	v_writelane_b32 v253, s38, 49
	v_writelane_b32 v253, s39, 50
	v_writelane_b32 v253, s40, 51
	v_writelane_b32 v253, s41, 52
	v_writelane_b32 v253, s42, 53
	v_writelane_b32 v253, s43, 54
	v_writelane_b32 v253, s44, 55
	v_writelane_b32 v253, s45, 56
	v_writelane_b32 v253, s46, 57
	v_writelane_b32 v253, s47, 58
	v_writelane_b32 v253, s48, 59
	v_writelane_b32 v253, s49, 60
	v_writelane_b32 v253, s50, 61
	v_writelane_b32 v253, s51, 62
	v_writelane_b32 v253, s2, 63
	s_mov_b64 s[42:43], s[10:11]
	s_load_dwordx16 s[4:19], s[0:1], 0x40
	v_writelane_b32 v254, s3, 0
	s_add_u32 s2, s30, 0x1620000
	s_addc_u32 s3, s31, 0
	v_writelane_b32 v254, s2, 1
	s_mov_b64 s[38:39], s[24:25]
	s_mov_b32 s51, 0
	v_writelane_b32 v254, s3, 2
	s_add_i32 s2, 32, 0x10000
	v_writelane_b32 v254, s2, 3
	s_add_i32 s2, 32, 0x11000
	v_writelane_b32 v254, s2, 4
	s_add_i32 s2, 32, 0x19800
	v_writelane_b32 v254, s2, 5
	s_add_i32 s2, 32, 0x20010
	v_writelane_b32 v254, s2, 6
	s_add_i32 s2, 32, 0xa100
	v_writelane_b32 v254, s2, 7
	s_add_i32 s2, 32, 0x500
	v_writelane_b32 v254, s2, 8
	v_cmp_eq_u32_e64 s[2:3], 0, v2
	s_movk_i32 s37, 0x1000
	s_movk_i32 s36, 0x1ff
	v_writelane_b32 v254, s2, 9
	s_add_i32 s33, 32, 0x22000
	s_add_i32 s34, 32, 0x24000
	v_writelane_b32 v254, s3, 10
	v_cmp_gt_u32_e64 s[2:3], 2, v2
	s_mov_b32 s47, 0x7f800000
	s_mov_b32 s49, 0x20000
	v_writelane_b32 v254, s2, 11
	s_mov_b32 s46, 0x4081e0d3
	s_mov_b32 s48, 0xc09de9e6
	v_writelane_b32 v254, s3, 12
	v_cmp_gt_u32_e64 s[2:3], 4, v2
	s_mov_b64 s[44:45], 0x800
	s_nop 0
	v_writelane_b32 v254, s2, 13
	s_nop 1
	v_writelane_b32 v254, s3, 14
	v_cmp_gt_u32_e64 s[2:3], 8, v2
	s_nop 1
	v_writelane_b32 v254, s2, 15
	s_nop 1
	v_writelane_b32 v254, s3, 16
	v_cmp_gt_u32_e64 s[2:3], 16, v2
	s_nop 1
	v_writelane_b32 v254, s2, 17
	s_nop 1
	v_writelane_b32 v254, s3, 18
	v_cmp_gt_u32_e64 s[2:3], 32, v2
	s_nop 1
	v_writelane_b32 v254, s2, 19
	s_nop 1
	v_writelane_b32 v254, s3, 20
	v_cmp_eq_u32_e64 s[2:3], 0, v0
	s_nop 1
	v_writelane_b32 v254, s2, 21
	s_nop 1
	v_writelane_b32 v254, s3, 22
	s_waitcnt lgkmcnt(0)
	v_writelane_b32 v254, s4, 23
	s_nop 1
	v_writelane_b32 v254, s5, 24
	v_writelane_b32 v254, s6, 25
	v_writelane_b32 v254, s7, 26
	v_writelane_b32 v254, s8, 27
	v_writelane_b32 v254, s9, 28
	v_writelane_b32 v254, s10, 29
	v_writelane_b32 v254, s11, 30
	v_writelane_b32 v254, s12, 31
	v_writelane_b32 v254, s13, 32
	v_writelane_b32 v254, s14, 33
	v_writelane_b32 v254, s15, 34
	v_writelane_b32 v254, s16, 35
	v_writelane_b32 v254, s17, 36
	v_writelane_b32 v254, s18, 37
	v_writelane_b32 v254, s19, 38
	s_load_dwordx16 s[4:19], s[0:1], 0x80
	s_waitcnt lgkmcnt(0)
	v_writelane_b32 v254, s4, 39
	s_nop 1
	v_writelane_b32 v254, s5, 40
	v_writelane_b32 v254, s6, 41
	v_writelane_b32 v254, s7, 42
	v_writelane_b32 v254, s8, 43
	v_writelane_b32 v254, s9, 44
	v_writelane_b32 v254, s10, 45
	v_writelane_b32 v254, s11, 46
	v_writelane_b32 v254, s12, 47
	v_writelane_b32 v254, s13, 48
	v_writelane_b32 v254, s14, 49
	v_writelane_b32 v254, s15, 50
	v_writelane_b32 v254, s16, 51
	v_writelane_b32 v254, s17, 52
	v_writelane_b32 v254, s18, 53
	v_writelane_b32 v254, s19, 54
	v_writelane_b32 v254, s64, 55
	s_nop 1
	v_writelane_b32 v254, s65, 56
	v_writelane_b32 v254, s38, 57
	s_nop 1
	v_writelane_b32 v254, s39, 58
	v_writelane_b32 v254, s42, 59
	s_nop 1
	v_writelane_b32 v254, s43, 60
	v_writelane_b32 v254, s84, 61
	s_nop 1
	v_writelane_b32 v254, s85, 62
	v_writelane_b32 v254, s86, 63
	s_nop 1
	v_writelane_b32 v255, s87, 0
	v_writelane_b32 v255, s35, 1
	s_mov_b32 s2, 0
	s_nop 0
	v_writelane_b32 v255, s2, 61
	s_branch .LBB0_10

.LBB0_1307:
	s_and_b64 vcc, exec, s[0:1]
	s_cbranch_vccz .LBB0_1335
	v_readlane_b32 s2, v255, 61
	s_nop 1
	s_cmp_lg_u32 s2, 0
	s_cbranch_scc1 .Lp1sw_normal
	v_readlane_b32 s2, v253, 36
	s_nop 1
	s_bitcmp1_b32 s2, 3
	s_cbranch_scc0 .Lp1sw_normal
	s_mov_b32 s2, 1
	s_nop 0
	v_writelane_b32 v255, s2, 61
	s_mov_b64 s[0:1], 0
	s_branch .LBB0_1319
.Lp1sw_normal:
	v_readlane_b32 s2, v251, 46
	v_readlane_b32 s3, v251, 47
	v_mov_b32_e32 v0, v179
	s_andn2_b64 vcc, exec, s[2:3]
	v_cndmask_b32_e64 v2, 0, 1, s[2:3]
	v_cmp_ne_u32_e64 s[0:1], 1, v2
	s_cbranch_vccnz .LBB0_1319
	v_lshlrev_b32_e32 v2, 2, v0
	v_and_b32_e32 v50, 0xfc, v2
	v_readlane_b32 s4, v253, 47
	s_waitcnt vmcnt(4)
	v_lshlrev_b32_e32 v14, 2, v50
	v_readlane_b32 s16, v253, 59
	v_readlane_b32 s17, v253, 60
	s_nop 4
	global_load_dwordx4 v[2:5], v14, s[16:17]
	global_load_dwordx4 v[6:9], v14, s[16:17] offset:1024
	global_load_dwordx4 v[10:13], v14, s[16:17] offset:2048
	s_nop 0
	global_load_dwordx4 v[14:17], v14, s[16:17] offset:3072
	v_cmp_lt_i32_e32 vcc, v248, v221
	v_ashrrev_i32_e32 v19, 6, v0
	v_readlane_b32 s2, v251, 20
	v_cndmask_b32_e32 v0, v249, v248, vcc
	v_cmp_lt_i32_e32 vcc, v220, v221
	v_lshlrev_b32_e32 v51, 2, v0
	v_readlane_b32 s3, v251, 21
	v_cndmask_b32_e32 v0, v249, v220, vcc
	v_cmp_lt_i32_e32 vcc, v236, v221
	v_lshlrev_b32_e32 v68, 2, v0
	s_load_dword s4, s[2:3], 0x0
	v_cndmask_b32_e32 v0, v249, v236, vcc
	v_cmp_lt_i32_e32 vcc, v237, v221
	v_lshlrev_b32_e32 v69, 2, v0
	v_readlane_b32 s2, v253, 33
	v_cndmask_b32_e32 v0, v249, v237, vcc
	v_cmp_lt_i32_e32 vcc, v216, v221
	v_lshlrev_b32_e32 v70, 2, v0
	v_readlane_b32 s5, v253, 48
	v_cndmask_b32_e32 v0, v249, v216, vcc
	v_cmp_lt_i32_e32 vcc, v250, v221
	v_lshlrev_b32_e32 v71, 2, v0
	v_readlane_b32 s6, v253, 49
	v_cndmask_b32_e32 v0, v249, v250, vcc
	v_lshlrev_b32_e32 v72, 2, v0
	v_or_b32_e32 v0, 0x100, v50
	v_or_b32_e32 v18, 0x200, v50
	v_or_b32_e32 v20, 0x300, v50
	s_waitcnt vmcnt(7)
	v_lshlrev_b32_e32 v22, 1, v50
	v_mov_b32_e32 v23, v1
	v_add_u32_e32 v54, s2, v19
	v_readlane_b32 s2, v253, 36
	v_lshl_add_u64 v[52:53], s[64:65], 0, v[22:23]
	s_waitcnt lgkmcnt(0)
	s_lshl_b32 s5, s4, 4
	v_lshlrev_b32_e32 v56, 2, v0
	v_lshlrev_b32_e32 v58, 2, v18
	v_lshlrev_b32_e32 v60, 2, v20
	s_mov_b32 s6, s2
	v_readlane_b32 s7, v253, 50
	v_readlane_b32 s8, v253, 51
	v_readlane_b32 s9, v253, 52
	v_readlane_b32 s10, v253, 53
	v_readlane_b32 s11, v253, 54
	v_readlane_b32 s12, v253, 55
	v_readlane_b32 s13, v253, 56
	v_readlane_b32 s14, v253, 57
	v_readlane_b32 s15, v253, 58
	v_readlane_b32 s18, v253, 61
	v_readlane_b32 s19, v253, 62
	v_readlane_b32 s3, v253, 37
	s_branch .LBB0_1311

.LBB0_1319:
	s_waitcnt vmcnt(0)
	v_readlane_b32 s2, v255, 61
	s_nop 1
	s_cmp_eq_u32 s2, 2
	s_cbranch_scc0 .Lp1sw_filter
	s_mov_b32 s2, 0
	s_nop 0
	v_writelane_b32 v255, s2, 61
	s_branch .LBB0_1335
.Lp1sw_filter:
	v_mov_b32_e32 v42, v179
	s_and_b64 vcc, exec, s[0:1]
	s_cbranch_vccnz .LBB0_1335
	s_movk_i32 s0, 0x800
	v_and_b32_e32 v43, 31, v42
	v_cmp_gt_i32_e64 s[52:53], s0, v42
	v_ashrrev_i32_e32 v0, 2, v42
	s_movk_i32 s0, 0x104
	v_and_b32_e32 v44, -8, v0
	v_and_b32_e32 v0, 0xffffffe0, v42
	v_mad_u32_u24 v45, v43, s0, 32
	s_add_i32 s0, 32, 0x8200
	v_add_u32_e32 v47, s0, v0
	v_readlane_b32 s0, v253, 36
	v_lshlrev_b32_e32 v46, 2, v42
	s_mov_b32 s8, s0
	v_readlane_b32 s1, v253, 37
	v_readfirstlane_b32 s2, v42
	s_cmp_ge_u32 s2, 0x100
	s_cbranch_scc0 .Lp1_np
	s_setprio 1

.LBB0_1335:
	s_setprio 0
	v_readlane_b32 s2, v255, 61
	s_nop 1
	s_cmp_eq_u32 s2, 1
	s_cbranch_scc0 .Lp1sw_done
	s_mov_b32 s2, 2
	s_nop 0
	v_writelane_b32 v255, s2, 61
	s_branch .Lp1sw_normal
